# MLA loop: segment heads start with resident-address LDS reads (loop-invariant K-fragment LDS address math hoisted to the preheader) on top of SGPR-base K/V LDS-DMA addressing
# speedup vs baseline: 1.0037x; 1.0037x over previous
.LBB0_2190:
	v_and_b32_e32 v50, 63, v192
	v_lshlrev_b32_e32 v52, 4, v50
	v_lshlrev_b32_e32 v51, 3, v50
	v_and_b32_e32 v52, 0xc0, v52
	v_lshlrev_b32_e32 v53, 1, v50
	v_and_or_b32 v52, v51, 24, v52
	v_and_b32_e32 v53, 32, v53
	v_and_b32_e32 v51, 0x100, v51
	v_or3_b32 v51, v52, v53, v51
	v_add_u32_e32 v209, 0, v51
	v_max_f32_e32 v51, v35, v35
	v_max_f32_e32 v52, v34, v34
	v_max_f32_e32 v51, v52, v51
	v_max3_f32 v51, v51, v36, v37
	v_max3_f32 v51, v51, v38, v39
	v_max3_f32 v51, v51, v40, v41
	v_max3_f32 v51, v51, v42, v43
	v_max3_f32 v51, v51, v44, v45
	v_max3_f32 v51, v51, v46, v47
	v_max3_f32 v51, v51, v48, v49
	v_max3_f32 v51, v51, v18, v19
	v_max3_f32 v51, v51, v20, v21
	v_max3_f32 v51, v51, v22, v23
	v_max3_f32 v51, v51, v24, v25
	v_max3_f32 v51, v51, v26, v27
	v_max3_f32 v51, v51, v28, v29
	v_max3_f32 v51, v51, v30, v31
	v_max3_f32 v51, v51, v32, v33
	v_mov_b32_e32 v52, v51
	s_nop 1
	v_permlane32_swap_b32_e32 v51, v52
	v_max_f32_e32 v52, v52, v52
	v_max_f32_e32 v51, v51, v51
	s_lshl_b32 s1, s1, 8
	v_max_f32_e32 v51, v51, v52
	s_lshl_b32 s0, s0, 2
	s_add_i32 s10, s1, 0
	v_add_f32_e32 v52, 0x7149f2ca, v51
	s_sub_i32 s21, 0x100, s0
	s_add_i32 s10, s10, 0x18000
	s_add_i32 s11, s11, -2.0
	v_cmp_ge_f32_e32 vcc, s83, v52
	v_max_f32_e32 v51, 0xf149f2ca, v51
	s_cmp_eq_u64 vcc, exec
	v_sub_f32_e32 v53, 0xf149f2ca, v51
	s_cselect_b64 vcc, -1, 0
	v_exp_f32_e32 v53, v53
	v_cndmask_b32_e32 v238, v51, v199, vcc
	v_sub_f32_e32 v34, v34, v238
	v_sub_f32_e32 v35, v35, v238
	v_sub_f32_e32 v36, v36, v238
	v_sub_f32_e32 v37, v37, v238
	v_sub_f32_e32 v38, v38, v238
	v_sub_f32_e32 v39, v39, v238
	v_sub_f32_e32 v40, v40, v238
	v_sub_f32_e32 v41, v41, v238
	v_sub_f32_e32 v42, v42, v238
	v_sub_f32_e32 v43, v43, v238
	v_sub_f32_e32 v44, v44, v238
	v_sub_f32_e32 v45, v45, v238
	v_sub_f32_e32 v46, v46, v238
	v_sub_f32_e32 v47, v47, v238
	v_sub_f32_e32 v48, v48, v238
	v_sub_f32_e32 v49, v49, v238
	v_exp_f32_e32 v82, v34
	v_exp_f32_e32 v83, v35
	v_exp_f32_e32 v84, v36
	v_exp_f32_e32 v85, v37
	v_exp_f32_e32 v86, v38
	v_exp_f32_e32 v87, v39
	v_exp_f32_e32 v88, v40
	v_exp_f32_e32 v89, v41
	v_exp_f32_e32 v90, v42
	v_exp_f32_e32 v91, v43
	v_exp_f32_e32 v92, v44
	v_exp_f32_e32 v93, v45
	v_exp_f32_e32 v94, v46
	v_exp_f32_e32 v95, v47
	v_exp_f32_e32 v96, v48
	v_exp_f32_e32 v97, v49
	s_add_i32 s2, s6, 0x3e45
	v_sub_f32_e32 v98, v18, v238
	s_waitcnt vmcnt(0)
	s_sub_i32 s22, 0xff, s0
	v_cmp_gt_u32_e64 s[0:1], 32, v50
	v_add_u32_e32 v18, s2, v14
	v_mov_b32_e32 v50, v1
	v_mov_b32_e32 v51, v1
	v_mov_b32_e32 v64, v1
	v_mov_b32_e32 v65, v1
	v_cndmask_b32_e64 v236, v53, 1.0, vcc
	v_sub_f32_e32 v113, v33, v238
	v_sub_f32_e32 v112, v32, v238
	v_sub_f32_e32 v111, v31, v238
	v_sub_f32_e32 v110, v30, v238
	v_sub_f32_e32 v109, v29, v238
	v_sub_f32_e32 v108, v28, v238
	v_sub_f32_e32 v107, v27, v238
	v_sub_f32_e32 v106, v26, v238
	v_sub_f32_e32 v105, v25, v238
	v_sub_f32_e32 v104, v24, v238
	v_sub_f32_e32 v103, v23, v238
	v_sub_f32_e32 v102, v22, v238
	v_sub_f32_e32 v101, v21, v238
	v_sub_f32_e32 v100, v20, v238
	v_sub_f32_e32 v99, v19, v238
	v_lshl_add_u32 v227, v17, 2, s10
	v_sub_u32_e32 v17, v18, v17
	v_mov_b32_e32 v52, v1
	v_mov_b32_e32 v53, v1
	v_mov_b32_e32 v54, v1
	v_mov_b32_e32 v55, v1
	v_mov_b32_e32 v56, v1
	v_mov_b32_e32 v57, v1
	v_mov_b32_e32 v58, v1
	v_mov_b32_e32 v59, v1
	v_mov_b32_e32 v60, v1
	v_mov_b32_e32 v61, v1
	v_mov_b32_e32 v62, v1
	v_mov_b32_e32 v63, v1
	v_mov_b64_e32 v[80:81], v[64:65]
	v_mov_b64_e32 v[34:35], v[50:51]
	v_mov_b64_e32 v[18:19], v[50:51]
	v_mov_b32_e32 v211, v1
	v_mov_b32_e32 v213, v1
	v_mov_b32_e32 v215, v1
	v_mov_b32_e32 v217, v1
	s_mov_b32 s20, 2
	v_lshl_add_u32 v228, v14, 2, s10
	v_subrev_u32_e32 v237, s8, v17
	s_mov_b32 s26, 0
	v_mov_b32_e32 v17, 0
	s_movk_i32 s23, 0xbf
	v_mov_b64_e32 v[78:79], v[62:63]
	v_mov_b64_e32 v[76:77], v[60:61]
	v_mov_b64_e32 v[74:75], v[58:59]
	v_mov_b64_e32 v[72:73], v[56:57]
	v_mov_b64_e32 v[70:71], v[54:55]
	v_mov_b64_e32 v[68:69], v[52:53]
	v_mov_b64_e32 v[66:67], v[50:51]
	v_mov_b64_e32 v[36:37], v[52:53]
	v_mov_b64_e32 v[38:39], v[54:55]
	v_mov_b64_e32 v[40:41], v[56:57]
	v_mov_b64_e32 v[42:43], v[58:59]
	v_mov_b64_e32 v[44:45], v[60:61]
	v_mov_b64_e32 v[46:47], v[62:63]
	v_mov_b64_e32 v[48:49], v[64:65]
	v_mov_b64_e32 v[20:21], v[52:53]
	v_mov_b64_e32 v[22:23], v[54:55]
	v_mov_b64_e32 v[24:25], v[56:57]
	v_mov_b64_e32 v[26:27], v[58:59]
	v_mov_b64_e32 v[28:29], v[60:61]
	v_mov_b64_e32 v[30:31], v[62:63]
	v_mov_b64_e32 v[32:33], v[64:65]
	v_readfirstlane_b32 s60, v204
	v_readfirstlane_b32 s61, v205
	v_readfirstlane_b32 s62, v206
	v_readfirstlane_b32 s63, v207
	v_mul_lo_u32 v248, v14, s84
	v_lshlrev_b32_e32 v247, 3, v14
	v_and_b32_e32 v247, 0x70, v247
	v_add_u32_e32 v249, 0x12000, v248
	v_add_u32_e32 v248, s19, v248
	v_xad_u32 v204, v247, v208, v249
	v_xad_u32 v206, v247, v229, v249
	v_xad_u32 v207, v247, v234, v249
	v_xad_u32 v211, v247, v235, v249
	v_xad_u32 v213, v247, v208, v248
	v_xad_u32 v215, v247, v229, v248
	v_xad_u32 v217, v247, v234, v248
	v_xad_u32 v245, v247, v235, v248
	s_waitcnt vmcnt(0) lgkmcnt(0)
	s_barrier
.LBB0_2191:
	s_add_i32 s24, 0, 0x12000
	ds_read_b128 v[114:117], v204 offset:0
	ds_read_b128 v[130:133], v204 offset:0x3000
	ds_read_b128 v[194:197], v206 offset:0
	v_exp_f32_e32 v98, v98
	ds_read_b128 v[186:189], v206 offset:0x3000
	s_waitcnt lgkmcnt(3)
	v_add_f32_e32 v134, 0, v82
	v_mfma_f32_32x32x16_bf16 v[114:129], v[114:117], v[178:181], 0
	ds_read_b128 v[182:185], v207 offset:0
	v_add_f32_e32 v190, 0, v98
	s_waitcnt lgkmcnt(3)
	s_sub_i32 s25, s23, 63
	v_exp_f32_e32 v99, v99
	v_add_f32_e32 v202, v134, v83
	v_mfma_f32_32x32x16_bf16 v[130:145], v[130:133], v[178:181], 0
	s_mul_hi_u32 s3, s25, 0x900
	v_add_f32_e32 v243, v190, v99
	ds_read_b128 v[190:193], v207 offset:0x3000
	s_mul_i32 s2, s25, 0x900
	s_add_u32 s64, s60, s2
	s_addc_u32 s65, s61, s3
	v_exp_f32_e32 v100, v100
	s_mov_b32 m0, s13
	s_nop 0
	global_load_lds_dwordx4 v0, s[64:65]
	s_waitcnt lgkmcnt(3)
	v_add_f32_e32 v244, v202, v84
	v_mfma_f32_32x32x16_bf16 v[114:129], v[194:197], v[174:177], v[114:129]
	v_add_f32_e32 v200, v243, v100
	ds_read_b128 v[194:197], v211 offset:0
	s_waitcnt lgkmcnt(3)
	s_mov_b32 m0, s14
	v_exp_f32_e32 v101, v101
	v_mfma_f32_32x32x16_bf16 v[130:145], v[186:189], v[174:177], v[130:145]
	v_add_f32_e32 v201, v244, v85
	ds_read_b128 v[186:189], v211 offset:0x3000
	v_add_f32_e32 v200, v200, v101
	s_waitcnt lgkmcnt(3)
	v_exp_f32_e32 v102, v102
	v_mfma_f32_32x32x16_bf16 v[114:129], v[182:185], v[170:173], v[114:129]
	v_add_f32_e32 v201, v201, v86
	ds_read_b128 v[182:185], v204 offset:0x80
	v_add_f32_e32 v200, v200, v102
	s_waitcnt lgkmcnt(3)
	s_mul_hi_u32 s3, s25, 0x600
	v_exp_f32_e32 v103, v103
	v_mfma_f32_32x32x16_bf16 v[130:145], v[190:193], v[170:173], v[130:145]
	v_add_f32_e32 v201, v201, v87
	ds_read_b128 v[190:193], v204 offset:0x3080
	v_add_f32_e32 v200, v200, v103
	global_load_lds_dwordx4 v210, s[64:65]
	v_exp_f32_e32 v104, v104
	s_waitcnt lgkmcnt(3)
	v_add_f32_e32 v201, v201, v88
	v_mfma_f32_32x32x16_bf16 v[114:129], v[194:197], v[166:169], v[114:129]
	v_add_f32_e32 v200, v200, v104
	ds_read_b128 v[194:197], v206 offset:0x80
	s_mov_b32 m0, s15
	s_waitcnt lgkmcnt(3)
	s_mul_i32 s2, s25, 0x600
	v_exp_f32_e32 v105, v105
	v_mfma_f32_32x32x16_bf16 v[130:145], v[186:189], v[166:169], v[130:145]
	v_add_f32_e32 v201, v201, v89
	ds_read_b128 v[186:189], v206 offset:0x3080
	v_add_f32_e32 v200, v200, v105
	s_waitcnt lgkmcnt(3)
	s_add_u32 s66, s62, s2
	s_addc_u32 s67, s63, s3
	v_exp_f32_e32 v106, v106
	v_mfma_f32_32x32x16_bf16 v[114:129], v[182:185], v[162:165], v[114:129]
	v_add_f32_e32 v201, v201, v90
	ds_read_b128 v[182:185], v207 offset:0x80
	v_add_f32_e32 v200, v200, v106
	s_waitcnt lgkmcnt(3)
	s_lshl_b32 s2, s26, 14
	v_exp_f32_e32 v107, v107
	v_mfma_f32_32x32x16_bf16 v[130:145], v[190:193], v[162:165], v[130:145]
	v_add_f32_e32 v201, v201, v91
	ds_read_b128 v[190:193], v207 offset:0x3080
	v_add_f32_e32 v200, v200, v107
	s_waitcnt lgkmcnt(3)
	s_add_i32 s3, s2, 0xffffc000
	v_exp_f32_e32 v108, v108
	v_mfma_f32_32x32x16_bf16 v[114:129], v[194:197], v[158:161], v[114:129]
	v_add_f32_e32 v222, v201, v92
	s_cmp_lg_u32 s26, 0
	v_add_f32_e32 v194, v200, v108
	ds_read_b128 v[200:203], v211 offset:0x80
	s_cselect_b32 s3, s3, 0x8000
	global_load_lds_dwordx4 v212, s[64:65]
	v_exp_f32_e32 v109, v109
	s_waitcnt lgkmcnt(3)
	v_add_f32_e32 v195, v222, v93
	v_mfma_f32_32x32x16_bf16 v[130:145], v[186:189], v[158:161], v[130:145]
	v_add_f32_e32 v186, v194, v109
	ds_read_b128 v[230:233], v211 offset:0x3080
	s_add_i32 s3, s12, s3
	s_waitcnt lgkmcnt(3)
	v_exp_f32_e32 v110, v110
	v_mfma_f32_32x32x16_bf16 v[114:129], v[182:185], v[154:157], v[114:129]
	v_add_f32_e32 v187, v195, v94
	ds_read_b128 v[182:185], v204 offset:0x100
	v_add_f32_e32 v186, v186, v110
	s_waitcnt lgkmcnt(3)
	s_mov_b32 m0, s3
	v_exp_f32_e32 v111, v111
	v_mfma_f32_32x32x16_bf16 v[130:145], v[190:193], v[154:157], v[130:145]
	v_add_f32_e32 v187, v187, v95
	ds_read_b128 v[194:197], v204 offset:0x3100
	v_add_f32_e32 v186, v186, v111
	s_waitcnt lgkmcnt(3)
	v_exp_f32_e32 v112, v112
	v_mfma_f32_32x32x16_bf16 v[114:129], v[200:203], v[150:153], v[114:129]
	v_add_f32_e32 v190, v187, v96
	s_sub_i32 s27, s23, 64
	v_add_f32_e32 v191, v186, v112
	ds_read_b128 v[186:189], v206 offset:0x100
	s_waitcnt lgkmcnt(3)
	v_exp_f32_e32 v113, v113
	v_mfma_f32_32x32x16_bf16 v[130:145], v[230:233], v[150:153], v[130:145]
	v_add_f32_e32 v222, v190, v97
	v_add_f32_e32 v223, v191, v113
	ds_read_b128 v[190:193], v206 offset:0x3100
	global_load_lds_dwordx4 v214, s[66:67]
	s_waitcnt lgkmcnt(3)
	s_add_i32 m0, s3, 0x2000
	v_mfma_f32_32x32x16_bf16 v[114:129], v[182:185], v[146:149], v[114:129]
	ds_read_b128 v[200:203], v207 offset:0x100
	v_cvt_pk_bf16_f32 v182, v82, v83
	v_cvt_pk_bf16_f32 v184, v86, v87
	s_add_i32 s3, s23, 0xffffff81
	v_permlane32_swap_b32_e32 v182, v184
	s_waitcnt lgkmcnt(3)
	s_cmp_le_i32 s27, s9
	v_mfma_f32_32x32x16_bf16 v[130:145], v[194:197], v[146:149], v[130:145]
	ds_read_b128 v[194:197], v207 offset:0x3100
	v_cvt_pk_bf16_f32 v183, v84, v85
	v_cvt_pk_bf16_f32 v185, v88, v89
	s_cselect_b64 s[28:29], -1, 0
	v_permlane32_swap_b32_e32 v183, v185
	s_waitcnt lgkmcnt(3)
	s_cmp_gt_i32 s3, s11
	v_mfma_f32_32x32x16_bf16 v[114:129], v[186:189], v[10:13], v[114:129]
	ds_read_b128 v[230:233], v211 offset:0x100
	v_cvt_pk_bf16_f32 v186, v90, v91
	v_cvt_pk_bf16_f32 v188, v94, v95
	s_cselect_b64 s[30:31], -1, 0
	v_permlane32_swap_b32_e32 v186, v188
	s_waitcnt lgkmcnt(3)
	s_and_b64 s[28:29], s[28:29], s[30:31]
	v_mfma_f32_32x32x16_bf16 v[130:145], v[190:193], v[10:13], v[130:145]
	ds_read_b128 v[218:221], v211 offset:0x3100
	v_cvt_pk_bf16_f32 v187, v92, v93
	v_cvt_pk_bf16_f32 v189, v96, v97
	s_and_b64 vcc, exec, s[28:29]
	v_permlane32_swap_b32_e32 v187, v189
	s_waitcnt lgkmcnt(3)
	v_cvt_pk_bf16_f32 v190, v98, v99
	v_cvt_pk_bf16_f32 v192, v102, v103
	v_mfma_f32_32x32x16_bf16 v[114:129], v[200:203], v[6:9], v[114:129]
	v_permlane32_swap_b32_e32 v190, v192
	global_load_lds_dwordx4 v216, s[66:67]
	s_waitcnt lgkmcnt(2)
	v_cvt_pk_bf16_f32 v191, v100, v101
	v_cvt_pk_bf16_f32 v193, v104, v105
	s_nop 0
	v_mfma_f32_32x32x16_bf16 v[130:145], v[194:197], v[6:9], v[130:145]
	v_permlane32_swap_b32_e32 v191, v193
	s_waitcnt lgkmcnt(1)
	v_cvt_pk_bf16_f32 v194, v106, v107
	v_cvt_pk_bf16_f32 v196, v110, v111
	v_mfma_f32_32x32x16_bf16 v[114:129], v[230:233], v[2:5], v[114:129]
	v_permlane32_swap_b32_e32 v194, v196
	s_waitcnt lgkmcnt(0)
	v_cvt_pk_bf16_f32 v195, v108, v109
	v_cvt_pk_bf16_f32 v197, v112, v113
	v_mfma_f32_32x32x16_bf16 v[130:145], v[218:221], v[2:5], v[130:145]
	v_permlane32_swap_b32_e32 v195, v197
	v_add_f32_e32 v222, v222, v223
	v_mov_b32_e32 v223, v222
	s_nop 1
	v_permlane32_swap_b32_e32 v222, v223
	s_cbranch_vccnz .LBB0_2193
	v_add_u32_e32 v82, 0x7b, v237
	v_cmp_gt_u32_e32 vcc, 2.0, v82
	v_add_u32_e32 v82, 0x5b, v237
	s_nop 0
	v_cndmask_b32_e32 v114, v16, v114, vcc
	v_cmp_gt_u32_e32 vcc, 2.0, v82
	v_add_u32_e32 v82, 0x7a, v237
	s_nop 0
	v_cndmask_b32_e32 v130, v16, v130, vcc
	v_cmp_gt_u32_e32 vcc, 2.0, v82
	v_add_u32_e32 v82, 0x5a, v237
	s_nop 0
	v_cndmask_b32_e32 v115, v16, v115, vcc
	v_cmp_gt_u32_e32 vcc, 2.0, v82
	v_add_u32_e32 v82, 0x79, v237
	s_nop 0
	v_cndmask_b32_e32 v131, v16, v131, vcc
	v_cmp_gt_u32_e32 vcc, 2.0, v82
	v_add_u32_e32 v82, 0x59, v237
	s_nop 0
	v_cndmask_b32_e32 v116, v16, v116, vcc
	v_cmp_gt_u32_e32 vcc, 2.0, v82
	v_add_u32_e32 v82, 0x78, v237
	s_nop 0
	v_cndmask_b32_e32 v132, v16, v132, vcc
	v_cmp_gt_u32_e32 vcc, 2.0, v82
	v_add_u32_e32 v82, 0x58, v237
	s_nop 0
	v_cndmask_b32_e32 v117, v16, v117, vcc
	v_cmp_gt_u32_e32 vcc, 2.0, v82
	v_add_u32_e32 v82, 0x73, v237
	s_nop 0
	v_cndmask_b32_e32 v133, v16, v133, vcc
	v_cmp_gt_u32_e32 vcc, 2.0, v82
	v_add_u32_e32 v82, 0x53, v237
	s_nop 0
	v_cndmask_b32_e32 v118, v16, v118, vcc
	v_cmp_gt_u32_e32 vcc, 2.0, v82
	v_add_u32_e32 v82, 0x72, v237
	s_nop 0
	v_cndmask_b32_e32 v134, v16, v134, vcc
	v_cmp_gt_u32_e32 vcc, 2.0, v82
	v_add_u32_e32 v82, 0x52, v237
	s_nop 0
	v_cndmask_b32_e32 v119, v16, v119, vcc
	v_cmp_gt_u32_e32 vcc, 2.0, v82
	v_add_u32_e32 v82, 0x71, v237
	s_nop 0
	v_cndmask_b32_e32 v135, v16, v135, vcc
	v_cmp_gt_u32_e32 vcc, 2.0, v82
	v_add_u32_e32 v82, 0x51, v237
	s_nop 0
	v_cndmask_b32_e32 v120, v16, v120, vcc
	v_cmp_gt_u32_e32 vcc, 2.0, v82
	v_add_u32_e32 v82, 0x70, v237
	s_nop 0
	v_cndmask_b32_e32 v136, v16, v136, vcc
	v_cmp_gt_u32_e32 vcc, 2.0, v82
	v_add_u32_e32 v82, 0x50, v237
	s_nop 0
	v_cndmask_b32_e32 v121, v16, v121, vcc
	v_cmp_gt_u32_e32 vcc, 2.0, v82
	v_add_u32_e32 v82, 0x6b, v237
	s_nop 0
	v_cndmask_b32_e32 v137, v16, v137, vcc
	v_cmp_gt_u32_e32 vcc, 2.0, v82
	v_add_u32_e32 v82, 0x4b, v237
	s_nop 0
	v_cndmask_b32_e32 v122, v16, v122, vcc
	v_cmp_gt_u32_e32 vcc, 2.0, v82
	v_add_u32_e32 v82, 0x6a, v237
	s_nop 0
	v_cndmask_b32_e32 v138, v16, v138, vcc
	v_cmp_gt_u32_e32 vcc, 2.0, v82
	v_add_u32_e32 v82, 0x4a, v237
	s_nop 0
	v_cndmask_b32_e32 v123, v16, v123, vcc
	v_cmp_gt_u32_e32 vcc, 2.0, v82
	v_add_u32_e32 v82, 0x69, v237
	s_nop 0
	v_cndmask_b32_e32 v139, v16, v139, vcc
	v_cmp_gt_u32_e32 vcc, 2.0, v82
	v_add_u32_e32 v82, 0x49, v237
	s_nop 0
	v_cndmask_b32_e32 v124, v16, v124, vcc
	v_cmp_gt_u32_e32 vcc, 2.0, v82
	v_add_u32_e32 v82, 0x68, v237
	s_nop 0
	v_cndmask_b32_e32 v140, v16, v140, vcc
	v_cmp_gt_u32_e32 vcc, 2.0, v82
	v_add_u32_e32 v82, 0x48, v237
	s_nop 0
	v_cndmask_b32_e32 v125, v16, v125, vcc
	v_cmp_gt_u32_e32 vcc, 2.0, v82
	v_add_u32_e32 v82, 0x63, v237
	s_nop 0
	v_cndmask_b32_e32 v141, v16, v141, vcc
	v_cmp_gt_u32_e32 vcc, 2.0, v82
	v_add_u32_e32 v82, 0x43, v237
	s_nop 0
	v_cndmask_b32_e32 v126, v16, v126, vcc
	v_cmp_gt_u32_e32 vcc, 2.0, v82
	v_add_u32_e32 v82, 0x62, v237
	s_nop 0
	v_cndmask_b32_e32 v142, v16, v142, vcc
	v_cmp_gt_u32_e32 vcc, 2.0, v82
	v_add_u32_e32 v82, 0x42, v237
	s_nop 0
	v_cndmask_b32_e32 v127, v16, v127, vcc
	v_cmp_gt_u32_e32 vcc, 2.0, v82
	v_add_u32_e32 v82, 0x61, v237
	s_nop 0
	v_cndmask_b32_e32 v143, v16, v143, vcc
	v_cmp_gt_u32_e32 vcc, 2.0, v82
	v_add_u32_e32 v82, 0x41, v237
	s_nop 0
	v_cndmask_b32_e32 v128, v16, v128, vcc
	v_cmp_gt_u32_e32 vcc, 2.0, v82
	v_add_u32_e32 v82, 0x60, v237
	s_nop 0
	v_cndmask_b32_e32 v144, v16, v144, vcc
	v_cmp_gt_u32_e32 vcc, 2.0, v82
	v_add_u32_e32 v82, 64, v237
	s_nop 0
	v_cndmask_b32_e32 v129, v16, v129, vcc
	v_cmp_gt_u32_e32 vcc, 2.0, v82
	s_nop 1
	v_cndmask_b32_e32 v145, v16, v145, vcc

.LBB0_2197:
	s_waitcnt vmcnt(0)
	s_waitcnt vmcnt(0) lgkmcnt(0)
	s_barrier
	v_exp_f32_e32 v130, v130
	ds_read_b128 v[82:85], v213 offset:0
	ds_read_b128 v[98:101], v213 offset:0x3000
	ds_read_b128 v[200:203], v215 offset:0
	ds_read_b128 v[190:193], v215 offset:0x3000
	v_add_f32_e32 v196, 0, v114
	s_waitcnt lgkmcnt(3)
	v_add_f32_e32 v197, 0, v130
	v_mfma_f32_32x32x16_bf16 v[82:97], v[82:85], v[178:181], 0
	ds_read_b128 v[182:185], v217 offset:0
	s_add_i32 s2, s26, 1
	s_cmp_lg_u32 s26, 2
	v_exp_f32_e32 v131, v131
	s_waitcnt lgkmcnt(3)
	s_cselect_b32 s26, s2, 0
	s_add_i32 s2, s20, 1
	v_mfma_f32_32x32x16_bf16 v[98:113], v[98:101], v[178:181], 0
	s_min_i32 s2, s2, s22
	ds_read_b128 v[186:189], v217 offset:0x3000
	v_add_f32_e32 v220, v196, v115
	v_add_f32_e32 v221, v197, v131
	s_lshl_b32 s27, s2, 6
	s_mul_i32 s68, s27, 0x900
	s_mul_hi_u32 s69, s27, 0x900
	s_add_u32 s68, s68, s60
	s_addc_u32 s69, s69, s61
	v_exp_f32_e32 v132, v132
	s_mov_b32 m0, s16
	s_nop 0
	global_load_lds_dwordx4 v0, s[68:69]
	s_waitcnt lgkmcnt(3)
	v_add_f32_e32 v243, v220, v116
	v_mfma_f32_32x32x16_bf16 v[82:97], v[200:203], v[174:177], v[82:97]
	v_add_f32_e32 v242, v221, v132
	ds_read_b128 v[200:203], v245 offset:0
	s_waitcnt lgkmcnt(3)
	s_mov_b32 m0, s17
	v_exp_f32_e32 v133, v133
	v_mfma_f32_32x32x16_bf16 v[98:113], v[190:193], v[174:177], v[98:113]
	v_add_f32_e32 v230, v243, v117
	ds_read_b128 v[190:193], v245 offset:0x3000
	v_add_f32_e32 v231, v242, v133
	s_waitcnt lgkmcnt(3)
	v_exp_f32_e32 v134, v134
	v_mfma_f32_32x32x16_bf16 v[82:97], v[182:185], v[170:173], v[82:97]
	v_add_f32_e32 v230, v230, v118
	ds_read_b128 v[182:185], v213 offset:0x80
	v_add_f32_e32 v231, v231, v134
	s_waitcnt lgkmcnt(3)
	s_mul_i32 s74, s27, 0x600
	s_mul_hi_u32 s75, s27, 0x600
	s_add_u32 s74, s74, s62
	s_addc_u32 s75, s75, s63
	v_exp_f32_e32 v135, v135
	v_mfma_f32_32x32x16_bf16 v[98:113], v[186:189], v[170:173], v[98:113]
	v_add_f32_e32 v230, v230, v119
	ds_read_b128 v[186:189], v213 offset:0x3080
	v_add_f32_e32 v231, v231, v135
	global_load_lds_dwordx4 v210, s[68:69]
	v_exp_f32_e32 v136, v136
	s_waitcnt lgkmcnt(3)
	v_add_f32_e32 v196, v230, v120
	v_mfma_f32_32x32x16_bf16 v[82:97], v[200:203], v[166:169], v[82:97]
	v_add_f32_e32 v197, v231, v136
	ds_read_b128 v[200:203], v215 offset:0x80
	s_mov_b32 m0, s18
	s_waitcnt lgkmcnt(3)
	s_lshl_b32 s2, s26, 14
	v_exp_f32_e32 v137, v137
	v_mfma_f32_32x32x16_bf16 v[98:113], v[190:193], v[166:169], v[98:113]
	v_add_f32_e32 v196, v196, v121
	ds_read_b128 v[190:193], v215 offset:0x3080
	v_add_f32_e32 v197, v197, v137
	s_waitcnt lgkmcnt(3)
	s_add_i32 s3, s2, 0xffffc000
	v_exp_f32_e32 v138, v138
	v_mfma_f32_32x32x16_bf16 v[82:97], v[182:185], v[162:165], v[82:97]
	v_add_f32_e32 v196, v196, v122
	ds_read_b128 v[182:185], v217 offset:0x80
	v_add_f32_e32 v197, v197, v138
	s_waitcnt lgkmcnt(3)
	s_cmp_lg_u32 s26, 0
	v_exp_f32_e32 v139, v139
	v_mfma_f32_32x32x16_bf16 v[98:113], v[186:189], v[162:165], v[98:113]
	v_add_f32_e32 v196, v196, v123
	ds_read_b128 v[186:189], v217 offset:0x3080
	v_add_f32_e32 v197, v197, v139
	s_waitcnt lgkmcnt(3)
	s_cselect_b32 s3, s3, 0x8000
	v_exp_f32_e32 v140, v140
	v_mfma_f32_32x32x16_bf16 v[82:97], v[200:203], v[158:161], v[82:97]
	v_add_f32_e32 v196, v196, v124
	ds_read_b128 v[200:203], v245 offset:0x80
	v_add_f32_e32 v197, v197, v140
	global_load_lds_dwordx4 v212, s[68:69]
	v_exp_f32_e32 v141, v141
	s_waitcnt lgkmcnt(3)
	v_add_f32_e32 v194, v196, v125
	v_mfma_f32_32x32x16_bf16 v[98:113], v[190:193], v[158:161], v[98:113]
	v_add_f32_e32 v195, v197, v141
	ds_read_b128 v[190:193], v245 offset:0x3080
	s_add_i32 s3, s12, s3
	s_waitcnt lgkmcnt(3)
	v_exp_f32_e32 v142, v142
	v_mfma_f32_32x32x16_bf16 v[82:97], v[182:185], v[154:157], v[82:97]
	v_add_f32_e32 v194, v194, v126
	ds_read_b128 v[182:185], v213 offset:0x100
	v_add_f32_e32 v195, v195, v142
	s_waitcnt lgkmcnt(3)
	s_mov_b32 m0, s3
	v_exp_f32_e32 v143, v143
	v_mfma_f32_32x32x16_bf16 v[98:113], v[186:189], v[154:157], v[98:113]
	v_add_f32_e32 v230, v194, v127
	v_add_f32_e32 v186, v195, v143
	ds_read_b128 v[194:197], v213 offset:0x3100
	s_waitcnt lgkmcnt(3)
	v_exp_f32_e32 v144, v144
	v_mfma_f32_32x32x16_bf16 v[82:97], v[200:203], v[150:153], v[82:97]
	v_add_f32_e32 v230, v230, v128
	v_add_f32_e32 v200, v186, v144
	ds_read_b128 v[186:189], v215 offset:0x100
	s_waitcnt lgkmcnt(3)
	v_exp_f32_e32 v145, v145
	v_mfma_f32_32x32x16_bf16 v[98:113], v[190:193], v[150:153], v[98:113]
	v_add_f32_e32 v241, v230, v129
	ds_read_b128 v[190:193], v215 offset:0x3100
	v_add_f32_e32 v242, v200, v145
	global_load_lds_dwordx4 v214, s[74:75]
	s_waitcnt lgkmcnt(3)
	s_add_i32 m0, s3, 0x2000
	v_mfma_f32_32x32x16_bf16 v[82:97], v[182:185], v[146:149], v[82:97]
	ds_read_b128 v[200:203], v217 offset:0x100
	v_cvt_pk_bf16_f32 v182, v114, v115
	v_cvt_pk_bf16_f32 v184, v118, v119
	s_cmp_le_i32 s23, s9
	v_permlane32_swap_b32_e32 v182, v184
	s_waitcnt lgkmcnt(3)
	s_cselect_b64 s[28:29], -1, 0
	v_mfma_f32_32x32x16_bf16 v[98:113], v[194:197], v[146:149], v[98:113]
	ds_read_b128 v[194:197], v217 offset:0x3100
	v_cvt_pk_bf16_f32 v183, v116, v117
	v_cvt_pk_bf16_f32 v185, v120, v121
	s_cmp_gt_i32 s25, s11
	v_permlane32_swap_b32_e32 v183, v185
	s_waitcnt lgkmcnt(3)
	s_cselect_b64 s[30:31], -1, 0
	v_mfma_f32_32x32x16_bf16 v[82:97], v[186:189], v[10:13], v[82:97]
	ds_read_b128 v[230:233], v245 offset:0x100
	v_cvt_pk_bf16_f32 v186, v122, v123
	v_cvt_pk_bf16_f32 v188, v126, v127
	s_and_b64 s[28:29], s[28:29], s[30:31]
	v_permlane32_swap_b32_e32 v186, v188
	s_waitcnt lgkmcnt(3)
	s_and_b64 vcc, exec, s[28:29]
	v_mfma_f32_32x32x16_bf16 v[98:113], v[190:193], v[10:13], v[98:113]
	ds_read_b128 v[218:221], v245 offset:0x3100
	v_cvt_pk_bf16_f32 v187, v124, v125
	v_cvt_pk_bf16_f32 v189, v128, v129
	s_nop 0
	v_permlane32_swap_b32_e32 v187, v189
	s_waitcnt lgkmcnt(3)
	v_cvt_pk_bf16_f32 v190, v130, v131
	v_cvt_pk_bf16_f32 v192, v134, v135
	v_mfma_f32_32x32x16_bf16 v[82:97], v[200:203], v[6:9], v[82:97]
	v_permlane32_swap_b32_e32 v190, v192
	global_load_lds_dwordx4 v216, s[74:75]
	s_waitcnt lgkmcnt(2)
	v_cvt_pk_bf16_f32 v191, v132, v133
	v_cvt_pk_bf16_f32 v193, v136, v137
	s_nop 0
	v_mfma_f32_32x32x16_bf16 v[98:113], v[194:197], v[6:9], v[98:113]
	v_permlane32_swap_b32_e32 v191, v193
	s_waitcnt lgkmcnt(1)
	v_cvt_pk_bf16_f32 v194, v138, v139
	v_cvt_pk_bf16_f32 v196, v142, v143
	v_mfma_f32_32x32x16_bf16 v[82:97], v[230:233], v[2:5], v[82:97]
	v_permlane32_swap_b32_e32 v194, v196
	s_waitcnt lgkmcnt(0)
	v_cvt_pk_bf16_f32 v195, v140, v141
	v_cvt_pk_bf16_f32 v197, v144, v145
	v_mfma_f32_32x32x16_bf16 v[98:113], v[218:221], v[2:5], v[98:113]
	v_permlane32_swap_b32_e32 v195, v197
	v_add_f32_e32 v115, v241, v242
	v_mov_b32_e32 v116, v115
	s_nop 1
	v_permlane32_swap_b32_e32 v115, v116
	s_cbranch_vccnz .LBB0_2199
	v_add_u32_e32 v114, 59, v237
	v_cmp_gt_u32_e32 vcc, 2.0, v114
	v_add_u32_e32 v114, 27, v237
	s_nop 0
	v_cndmask_b32_e32 v82, v16, v82, vcc
	v_cmp_gt_u32_e32 vcc, 2.0, v114
	v_add_u32_e32 v114, 58, v237
	s_nop 0
	v_cndmask_b32_e32 v98, v16, v98, vcc
	v_cmp_gt_u32_e32 vcc, 2.0, v114
	v_add_u32_e32 v114, 26, v237
	s_nop 0
	v_cndmask_b32_e32 v83, v16, v83, vcc
	v_cmp_gt_u32_e32 vcc, 2.0, v114
	v_add_u32_e32 v114, 57, v237
	s_nop 0
	v_cndmask_b32_e32 v99, v16, v99, vcc
	v_cmp_gt_u32_e32 vcc, 2.0, v114
	v_add_u32_e32 v114, 25, v237
	s_nop 0
	v_cndmask_b32_e32 v84, v16, v84, vcc
	v_cmp_gt_u32_e32 vcc, 2.0, v114
	v_add_u32_e32 v114, 56, v237
	s_nop 0
	v_cndmask_b32_e32 v100, v16, v100, vcc
	v_cmp_gt_u32_e32 vcc, 2.0, v114
	v_add_u32_e32 v114, 24, v237
	s_nop 0
	v_cndmask_b32_e32 v85, v16, v85, vcc
	v_cmp_gt_u32_e32 vcc, 2.0, v114
	v_add_u32_e32 v114, 51, v237
	s_nop 0
	v_cndmask_b32_e32 v101, v16, v101, vcc
	v_cmp_gt_u32_e32 vcc, 2.0, v114
	v_add_u32_e32 v114, 19, v237
	s_nop 0
	v_cndmask_b32_e32 v86, v16, v86, vcc
	v_cmp_gt_u32_e32 vcc, 2.0, v114
	v_add_u32_e32 v114, 50, v237
	s_nop 0
	v_cndmask_b32_e32 v102, v16, v102, vcc
	v_cmp_gt_u32_e32 vcc, 2.0, v114
	v_add_u32_e32 v114, 18, v237
	s_nop 0
	v_cndmask_b32_e32 v87, v16, v87, vcc
	v_cmp_gt_u32_e32 vcc, 2.0, v114
	v_add_u32_e32 v114, 49, v237
	s_nop 0
	v_cndmask_b32_e32 v103, v16, v103, vcc
	v_cmp_gt_u32_e32 vcc, 2.0, v114
	v_add_u32_e32 v114, 17, v237
	s_nop 0
	v_cndmask_b32_e32 v88, v16, v88, vcc
	v_cmp_gt_u32_e32 vcc, 2.0, v114
	v_add_u32_e32 v114, 48, v237
	s_nop 0
	v_cndmask_b32_e32 v104, v16, v104, vcc
	v_cmp_gt_u32_e32 vcc, 2.0, v114
	v_add_u32_e32 v114, 16, v237
	s_nop 0
	v_cndmask_b32_e32 v89, v16, v89, vcc
	v_cmp_gt_u32_e32 vcc, 2.0, v114
	v_add_u32_e32 v114, 43, v237
	s_nop 0
	v_cndmask_b32_e32 v105, v16, v105, vcc
	v_cmp_gt_u32_e32 vcc, 2.0, v114
	v_add_u32_e32 v114, 11, v237
	s_nop 0
	v_cndmask_b32_e32 v90, v16, v90, vcc
	v_cmp_gt_u32_e32 vcc, 2.0, v114
	v_add_u32_e32 v114, 42, v237
	s_nop 0
	v_cndmask_b32_e32 v106, v16, v106, vcc
	v_cmp_gt_u32_e32 vcc, 2.0, v114
	v_add_u32_e32 v114, 10, v237
	s_nop 0
	v_cndmask_b32_e32 v91, v16, v91, vcc
	v_cmp_gt_u32_e32 vcc, 2.0, v114
	v_add_u32_e32 v114, 41, v237
	s_nop 0
	v_cndmask_b32_e32 v107, v16, v107, vcc
	v_cmp_gt_u32_e32 vcc, 2.0, v114
	v_add_u32_e32 v114, 9, v237
	s_nop 0
	v_cndmask_b32_e32 v92, v16, v92, vcc
	v_cmp_gt_u32_e32 vcc, 2.0, v114
	v_add_u32_e32 v114, 40, v237
	s_nop 0
	v_cndmask_b32_e32 v108, v16, v108, vcc
	v_cmp_gt_u32_e32 vcc, 2.0, v114
	v_add_u32_e32 v114, 8, v237
	s_nop 0
	v_cndmask_b32_e32 v93, v16, v93, vcc
	v_cmp_gt_u32_e32 vcc, 2.0, v114
	v_add_u32_e32 v114, 35, v237
	s_nop 0
	v_cndmask_b32_e32 v109, v16, v109, vcc
	v_cmp_gt_u32_e32 vcc, 2.0, v114
	v_add_u32_e32 v114, 3, v237
	s_nop 0
	v_cndmask_b32_e32 v94, v16, v94, vcc
	v_cmp_gt_u32_e32 vcc, 2.0, v114
	v_add_u32_e32 v114, 34, v237
	s_nop 0
	v_cndmask_b32_e32 v110, v16, v110, vcc
	v_cmp_gt_u32_e32 vcc, 2.0, v114
	v_add_u32_e32 v114, 2, v237
	s_nop 0
	v_cndmask_b32_e32 v95, v16, v95, vcc
	v_cmp_gt_u32_e32 vcc, 2.0, v114
	v_add_u32_e32 v114, 33, v237
	s_nop 0
	v_cndmask_b32_e32 v111, v16, v111, vcc
	v_cmp_gt_u32_e32 vcc, 2.0, v114
	v_add_u32_e32 v114, 1, v237
	s_nop 0
	v_cndmask_b32_e32 v96, v16, v96, vcc
	v_cmp_gt_u32_e32 vcc, 2.0, v114
	v_add_u32_e32 v114, 32, v237
	s_nop 0
	v_cndmask_b32_e32 v112, v16, v112, vcc
	v_cmp_gt_u32_e32 vcc, 2.0, v114
	s_nop 1
	v_cndmask_b32_e32 v97, v16, v97, vcc
	v_cmp_gt_u32_e32 vcc, 2.0, v237
	s_nop 1
	v_cndmask_b32_e32 v113, v16, v113, vcc
